# scan chunk body v2: next-pair LDS reads interleaved one per 3 VALU with counted lgkmcnt waits
# baseline (speedup 1.0000x reference)
.LBB0_1092:
	s_mov_b64 s[92:93], -1
	s_and_b64 vcc, exec, s[88:89]
	s_cbranch_vccz .LBB0_1098
	s_bitcmp1_b32 s9, 0
	s_cselect_b32 s7, 0xb200, 0
	s_add_i32 s26, s7, 0
	s_mov_b64 s[82:83], s[96:97]
	s_mov_b32 s84, s80
	v_lshl_add_u32 v174, v102, 2, s26
	v_mov_b32_e32 v175, s26
	v_add_u32_e32 v163, s26, v160
	v_mov_b64_e32 v[144:145], v[140:141]
	v_mov_b64_e32 v[146:147], v[142:143]
	v_mov_b32_e32 v162, v111
	ds_read_b128 v[0:3], v174 offset:0
	ds_read_b128 v[4:7], v174 offset:256
	ds_read_b128 v[8:11], v174 offset:512
	ds_read_b128 v[24:27], v174 offset:1536
	ds_read_b32 v40, v163 offset:2304
	ds_read_b32 v41, v163 offset:2560
	ds_read_b128 v[32:35], v174 offset:2048
	ds_read_b128 v[36:39], v175 offset:2816
	ds_read_b128 v[20:23], v174 offset:1280
	ds_read_b128 v[28:31], v174 offset:1792
	ds_read_b128 v[16:19], v174 offset:1024
	ds_read_b128 v[12:15], v174 offset:768
	s_waitcnt lgkmcnt(9)
	v_pk_mul_f32 v[96:97], v[144:145], v[50:51]
	v_pk_mul_f32 v[98:99], v[144:145], v[0:1]
	v_pk_mul_f32 v[100:101], v[144:145], v[4:5]
	v_pk_mul_f32 v[172:173], v[144:145], v[8:9]
	v_pk_fma_f32 v[96:97], v[146:147], v[52:53], v[96:97]
	v_pk_fma_f32 v[98:99], v[146:147], v[2:3], v[98:99]
	ds_read_b128 v[54:57], v174 offset:2848
	v_pk_fma_f32 v[100:101], v[146:147], v[6:7], v[100:101]
	v_pk_fma_f32 v[172:173], v[146:147], v[10:11], v[172:173]
	v_add_f32_e32 v168, v96, v97
	ds_read_b128 v[58:61], v174 offset:3104
	v_add_f32_e32 v166, v98, v99
	v_add_f32_e32 v169, v100, v101
	v_add_f32_e32 v170, v172, v173
	ds_read_b128 v[62:65], v174 offset:3360
	v_add_f32_dpp v168, v168, v168 row_mirror row_mask:0xf bank_mask:0xf bound_ctrl:1
	v_add_f32_dpp v166, v166, v166 row_mirror row_mask:0xf bank_mask:0xf bound_ctrl:1
	v_add_f32_dpp v169, v169, v169 row_mirror row_mask:0xf bank_mask:0xf bound_ctrl:1
	ds_read_b128 v[78:81], v174 offset:4384
	v_add_f32_dpp v170, v170, v170 row_mirror row_mask:0xf bank_mask:0xf bound_ctrl:1
	s_waitcnt lgkmcnt(11)
	v_pk_mul_f32 v[148:149], v[24:25], v[40:41] op_sel_hi:[1,0]
	v_pk_mul_f32 v[150:151], v[26:27], v[40:41] op_sel_hi:[1,0]
	ds_read_b32 v94, v163 offset:5152
	v_add_f32_dpp v168, v168, v168 row_half_mirror row_mask:0xf bank_mask:0xf bound_ctrl:1
	v_add_f32_dpp v166, v166, v166 row_half_mirror row_mask:0xf bank_mask:0xf bound_ctrl:1
	v_add_f32_dpp v169, v169, v169 row_half_mirror row_mask:0xf bank_mask:0xf bound_ctrl:1
	ds_read_b32 v95, v163 offset:5408
	v_add_f32_dpp v170, v170, v170 row_half_mirror row_mask:0xf bank_mask:0xf bound_ctrl:1
	s_waitcnt lgkmcnt(11)
	v_pk_fma_f32 v[148:149], v[32:33], v[40:41], v[148:149] op_sel:[0,1,0] op_sel_hi:[1,1,1]
	v_pk_fma_f32 v[150:151], v[34:35], v[40:41], v[150:151] op_sel:[0,1,0] op_sel_hi:[1,1,1]
	ds_read_b128 v[86:89], v174 offset:4896
	v_add_f32_dpp v168, v168, v168 quad_perm:[1,0,3,2] row_mask:0xf bank_mask:0xf bound_ctrl:1
	v_add_f32_dpp v166, v166, v166 quad_perm:[1,0,3,2] row_mask:0xf bank_mask:0xf bound_ctrl:1
	v_add_f32_dpp v169, v169, v169 quad_perm:[1,0,3,2] row_mask:0xf bank_mask:0xf bound_ctrl:1
	ds_read_b128 v[90:93], v175 offset:5664
	v_add_f32_dpp v170, v170, v170 quad_perm:[1,0,3,2] row_mask:0xf bank_mask:0xf bound_ctrl:1
	v_add_f32_dpp v168, v168, v168 quad_perm:[2,3,0,1] row_mask:0xf bank_mask:0xf bound_ctrl:1
	v_add_f32_dpp v166, v166, v166 quad_perm:[2,3,0,1] row_mask:0xf bank_mask:0xf bound_ctrl:1
	ds_read_b128 v[74:77], v174 offset:4128
	v_add_f32_dpp v169, v169, v169 quad_perm:[2,3,0,1] row_mask:0xf bank_mask:0xf bound_ctrl:1
	v_add_f32_dpp v170, v170, v170 quad_perm:[2,3,0,1] row_mask:0xf bank_mask:0xf bound_ctrl:1
	s_waitcnt lgkmcnt(13)
	v_fma_f32 v164, v40, v37, v169
	ds_read_b128 v[82:85], v174 offset:4640
	v_fma_f32 v171, v40, v39, v170
	s_waitcnt lgkmcnt(13)
	v_pk_fma_f32 v[148:149], v[20:21], v[166:167], v[148:149] op_sel_hi:[1,0,1]
	v_fma_f32 v167, v166, v36, v164
	ds_read_b128 v[70:73], v174 offset:3872
	v_pk_fma_f32 v[150:151], v[22:23], v[166:167], v[150:151] op_sel_hi:[1,0,1]
	v_fma_f32 v171, v166, v38, v171
	v_cndmask_b32_e64 v162, v162, v168, s[46:47]
	ds_read_b128 v[66:69], v174 offset:3616
	s_lshl_b32 s6, s9, 1
	s_cmp_eq_u32 s6, 0
	s_cbranch_scc1 .Lscan_noy0
	s_add_i32 s6, s6, -1
	s_and_b32 s6, s6, 7
	s_lshl_b32 s6, s6, 10
	v_add_u32_e32 v161, s6, v156
	ds_write_b32 v161, v162
.Lscan_noy0:
	s_waitcnt lgkmcnt(14)
	v_pk_fma_f32 v[148:149], v[28:29], v[166:167], v[148:149] op_sel:[0,1,0] op_sel_hi:[1,1,1]
	v_pk_fma_f32 v[150:151], v[30:31], v[166:167], v[150:151] op_sel:[0,1,0] op_sel_hi:[1,1,1]
	v_cndmask_b32_e64 v162, v162, v171, s[38:39]
	s_waitcnt lgkmcnt(13)
	v_pk_fma_f32 v[144:145], v[144:145], v[16:17], v[148:149]
	v_pk_fma_f32 v[146:147], v[146:147], v[18:19], v[150:151]
	s_waitcnt lgkmcnt(9)
	v_pk_mul_f32 v[96:97], v[144:145], v[12:13]
	v_pk_mul_f32 v[98:99], v[144:145], v[54:55]
	v_pk_mul_f32 v[100:101], v[144:145], v[58:59]
	v_pk_mul_f32 v[172:173], v[144:145], v[62:63]
	v_pk_fma_f32 v[96:97], v[146:147], v[14:15], v[96:97]
	v_pk_fma_f32 v[98:99], v[146:147], v[56:57], v[98:99]
	ds_read_b128 v[0:3], v174 offset:5696
	v_pk_fma_f32 v[100:101], v[146:147], v[60:61], v[100:101]
	v_pk_fma_f32 v[172:173], v[146:147], v[64:65], v[172:173]
	v_add_f32_e32 v168, v96, v97
	ds_read_b128 v[4:7], v174 offset:5952
	v_add_f32_e32 v166, v98, v99
	v_add_f32_e32 v169, v100, v101
	v_add_f32_e32 v170, v172, v173
	ds_read_b128 v[8:11], v174 offset:6208
	v_add_f32_dpp v168, v168, v168 row_mirror row_mask:0xf bank_mask:0xf bound_ctrl:1
	v_add_f32_dpp v166, v166, v166 row_mirror row_mask:0xf bank_mask:0xf bound_ctrl:1
	v_add_f32_dpp v169, v169, v169 row_mirror row_mask:0xf bank_mask:0xf bound_ctrl:1
	ds_read_b128 v[24:27], v174 offset:7232
	v_add_f32_dpp v170, v170, v170 row_mirror row_mask:0xf bank_mask:0xf bound_ctrl:1
	s_waitcnt lgkmcnt(11)
	v_pk_mul_f32 v[148:149], v[78:79], v[94:95] op_sel_hi:[1,0]
	v_pk_mul_f32 v[150:151], v[80:81], v[94:95] op_sel_hi:[1,0]
	ds_read_b32 v40, v163 offset:8000
	v_add_f32_dpp v168, v168, v168 row_half_mirror row_mask:0xf bank_mask:0xf bound_ctrl:1
	v_add_f32_dpp v166, v166, v166 row_half_mirror row_mask:0xf bank_mask:0xf bound_ctrl:1
	v_add_f32_dpp v169, v169, v169 row_half_mirror row_mask:0xf bank_mask:0xf bound_ctrl:1
	ds_read_b32 v41, v163 offset:8256
	v_add_f32_dpp v170, v170, v170 row_half_mirror row_mask:0xf bank_mask:0xf bound_ctrl:1
	s_waitcnt lgkmcnt(11)
	v_pk_fma_f32 v[148:149], v[86:87], v[94:95], v[148:149] op_sel:[0,1,0] op_sel_hi:[1,1,1]
	v_pk_fma_f32 v[150:151], v[88:89], v[94:95], v[150:151] op_sel:[0,1,0] op_sel_hi:[1,1,1]
	ds_read_b128 v[32:35], v174 offset:7744
	v_add_f32_dpp v168, v168, v168 quad_perm:[1,0,3,2] row_mask:0xf bank_mask:0xf bound_ctrl:1
	v_add_f32_dpp v166, v166, v166 quad_perm:[1,0,3,2] row_mask:0xf bank_mask:0xf bound_ctrl:1
	v_add_f32_dpp v169, v169, v169 quad_perm:[1,0,3,2] row_mask:0xf bank_mask:0xf bound_ctrl:1
	ds_read_b128 v[36:39], v175 offset:8512
	v_add_f32_dpp v170, v170, v170 quad_perm:[1,0,3,2] row_mask:0xf bank_mask:0xf bound_ctrl:1
	v_add_f32_dpp v168, v168, v168 quad_perm:[2,3,0,1] row_mask:0xf bank_mask:0xf bound_ctrl:1
	v_add_f32_dpp v166, v166, v166 quad_perm:[2,3,0,1] row_mask:0xf bank_mask:0xf bound_ctrl:1
	ds_read_b128 v[20:23], v174 offset:6976
	v_add_f32_dpp v169, v169, v169 quad_perm:[2,3,0,1] row_mask:0xf bank_mask:0xf bound_ctrl:1
	v_add_f32_dpp v170, v170, v170 quad_perm:[2,3,0,1] row_mask:0xf bank_mask:0xf bound_ctrl:1
	s_waitcnt lgkmcnt(13)
	v_fma_f32 v164, v94, v91, v169
	ds_read_b128 v[28:31], v174 offset:7488
	v_fma_f32 v171, v94, v93, v170
	s_waitcnt lgkmcnt(13)
	v_pk_fma_f32 v[148:149], v[74:75], v[166:167], v[148:149] op_sel_hi:[1,0,1]
	v_fma_f32 v167, v166, v90, v164
	ds_read_b128 v[16:19], v174 offset:6720
	v_pk_fma_f32 v[150:151], v[76:77], v[166:167], v[150:151] op_sel_hi:[1,0,1]
	v_fma_f32 v171, v166, v92, v171
	v_cndmask_b32_e64 v162, v162, v168, s[48:49]
	ds_read_b128 v[12:15], v174 offset:6464
	s_waitcnt lgkmcnt(14)
	v_pk_fma_f32 v[148:149], v[82:83], v[166:167], v[148:149] op_sel:[0,1,0] op_sel_hi:[1,1,1]
	v_pk_fma_f32 v[150:151], v[84:85], v[166:167], v[150:151] op_sel:[0,1,0] op_sel_hi:[1,1,1]
	v_cndmask_b32_e64 v162, v162, v171, s[50:51]
	s_waitcnt lgkmcnt(13)
	v_pk_fma_f32 v[144:145], v[144:145], v[70:71], v[148:149]
	v_pk_fma_f32 v[146:147], v[146:147], v[72:73], v[150:151]
	s_waitcnt lgkmcnt(9)
	v_pk_mul_f32 v[96:97], v[144:145], v[66:67]
	v_pk_mul_f32 v[98:99], v[144:145], v[0:1]
	v_pk_mul_f32 v[100:101], v[144:145], v[4:5]
	v_pk_mul_f32 v[172:173], v[144:145], v[8:9]
	v_pk_fma_f32 v[96:97], v[146:147], v[68:69], v[96:97]
	v_pk_fma_f32 v[98:99], v[146:147], v[2:3], v[98:99]
	ds_read_b128 v[54:57], v174 offset:8544
	v_pk_fma_f32 v[100:101], v[146:147], v[6:7], v[100:101]
	v_pk_fma_f32 v[172:173], v[146:147], v[10:11], v[172:173]
	v_add_f32_e32 v168, v96, v97
	ds_read_b128 v[58:61], v174 offset:8800
	v_add_f32_e32 v166, v98, v99
	v_add_f32_e32 v169, v100, v101
	v_add_f32_e32 v170, v172, v173
	ds_read_b128 v[62:65], v174 offset:9056
	v_add_f32_dpp v168, v168, v168 row_mirror row_mask:0xf bank_mask:0xf bound_ctrl:1
	v_add_f32_dpp v166, v166, v166 row_mirror row_mask:0xf bank_mask:0xf bound_ctrl:1
	v_add_f32_dpp v169, v169, v169 row_mirror row_mask:0xf bank_mask:0xf bound_ctrl:1
	ds_read_b128 v[78:81], v174 offset:10080
	v_add_f32_dpp v170, v170, v170 row_mirror row_mask:0xf bank_mask:0xf bound_ctrl:1
	s_waitcnt lgkmcnt(11)
	v_pk_mul_f32 v[148:149], v[24:25], v[40:41] op_sel_hi:[1,0]
	v_pk_mul_f32 v[150:151], v[26:27], v[40:41] op_sel_hi:[1,0]
	ds_read_b32 v94, v163 offset:10848
	v_add_f32_dpp v168, v168, v168 row_half_mirror row_mask:0xf bank_mask:0xf bound_ctrl:1
	v_add_f32_dpp v166, v166, v166 row_half_mirror row_mask:0xf bank_mask:0xf bound_ctrl:1
	v_add_f32_dpp v169, v169, v169 row_half_mirror row_mask:0xf bank_mask:0xf bound_ctrl:1
	ds_read_b32 v95, v163 offset:11104
	v_add_f32_dpp v170, v170, v170 row_half_mirror row_mask:0xf bank_mask:0xf bound_ctrl:1
	s_waitcnt lgkmcnt(11)
	v_pk_fma_f32 v[148:149], v[32:33], v[40:41], v[148:149] op_sel:[0,1,0] op_sel_hi:[1,1,1]
	v_pk_fma_f32 v[150:151], v[34:35], v[40:41], v[150:151] op_sel:[0,1,0] op_sel_hi:[1,1,1]
	ds_read_b128 v[86:89], v174 offset:10592
	v_add_f32_dpp v168, v168, v168 quad_perm:[1,0,3,2] row_mask:0xf bank_mask:0xf bound_ctrl:1
	v_add_f32_dpp v166, v166, v166 quad_perm:[1,0,3,2] row_mask:0xf bank_mask:0xf bound_ctrl:1
	v_add_f32_dpp v169, v169, v169 quad_perm:[1,0,3,2] row_mask:0xf bank_mask:0xf bound_ctrl:1
	ds_read_b128 v[90:93], v175 offset:11360
	v_add_f32_dpp v170, v170, v170 quad_perm:[1,0,3,2] row_mask:0xf bank_mask:0xf bound_ctrl:1
	v_add_f32_dpp v168, v168, v168 quad_perm:[2,3,0,1] row_mask:0xf bank_mask:0xf bound_ctrl:1
	v_add_f32_dpp v166, v166, v166 quad_perm:[2,3,0,1] row_mask:0xf bank_mask:0xf bound_ctrl:1
	ds_read_b128 v[74:77], v174 offset:9824
	v_add_f32_dpp v169, v169, v169 quad_perm:[2,3,0,1] row_mask:0xf bank_mask:0xf bound_ctrl:1
	v_add_f32_dpp v170, v170, v170 quad_perm:[2,3,0,1] row_mask:0xf bank_mask:0xf bound_ctrl:1
	s_waitcnt lgkmcnt(13)
	v_fma_f32 v164, v40, v37, v169
	ds_read_b128 v[82:85], v174 offset:10336
	v_fma_f32 v171, v40, v39, v170
	s_waitcnt lgkmcnt(13)
	v_pk_fma_f32 v[148:149], v[20:21], v[166:167], v[148:149] op_sel_hi:[1,0,1]
	v_fma_f32 v167, v166, v36, v164
	ds_read_b128 v[70:73], v174 offset:9568
	v_pk_fma_f32 v[150:151], v[22:23], v[166:167], v[150:151] op_sel_hi:[1,0,1]
	v_fma_f32 v171, v166, v38, v171
	v_cndmask_b32_e64 v162, v162, v168, s[52:53]
	ds_read_b128 v[66:69], v174 offset:9312
	s_waitcnt lgkmcnt(14)
	v_pk_fma_f32 v[148:149], v[28:29], v[166:167], v[148:149] op_sel:[0,1,0] op_sel_hi:[1,1,1]
	v_pk_fma_f32 v[150:151], v[30:31], v[166:167], v[150:151] op_sel:[0,1,0] op_sel_hi:[1,1,1]
	v_cndmask_b32_e64 v162, v162, v171, s[54:55]
	s_waitcnt lgkmcnt(13)
	v_pk_fma_f32 v[144:145], v[144:145], v[16:17], v[148:149]
	v_pk_fma_f32 v[146:147], v[146:147], v[18:19], v[150:151]
	s_waitcnt lgkmcnt(9)
	v_pk_mul_f32 v[96:97], v[144:145], v[12:13]
	v_pk_mul_f32 v[98:99], v[144:145], v[54:55]
	v_pk_mul_f32 v[100:101], v[144:145], v[58:59]
	v_pk_mul_f32 v[172:173], v[144:145], v[62:63]
	v_pk_fma_f32 v[96:97], v[146:147], v[14:15], v[96:97]
	v_pk_fma_f32 v[98:99], v[146:147], v[56:57], v[98:99]
	ds_read_b128 v[0:3], v174 offset:11392
	v_pk_fma_f32 v[100:101], v[146:147], v[60:61], v[100:101]
	v_pk_fma_f32 v[172:173], v[146:147], v[64:65], v[172:173]
	v_add_f32_e32 v168, v96, v97
	ds_read_b128 v[4:7], v174 offset:11648
	v_add_f32_e32 v166, v98, v99
	v_add_f32_e32 v169, v100, v101
	v_add_f32_e32 v170, v172, v173
	ds_read_b128 v[8:11], v174 offset:11904
	v_add_f32_dpp v168, v168, v168 row_mirror row_mask:0xf bank_mask:0xf bound_ctrl:1
	v_add_f32_dpp v166, v166, v166 row_mirror row_mask:0xf bank_mask:0xf bound_ctrl:1
	v_add_f32_dpp v169, v169, v169 row_mirror row_mask:0xf bank_mask:0xf bound_ctrl:1
	ds_read_b128 v[24:27], v174 offset:12928
	v_add_f32_dpp v170, v170, v170 row_mirror row_mask:0xf bank_mask:0xf bound_ctrl:1
	s_waitcnt lgkmcnt(11)
	v_pk_mul_f32 v[148:149], v[78:79], v[94:95] op_sel_hi:[1,0]
	v_pk_mul_f32 v[150:151], v[80:81], v[94:95] op_sel_hi:[1,0]
	ds_read_b32 v40, v163 offset:13696
	v_add_f32_dpp v168, v168, v168 row_half_mirror row_mask:0xf bank_mask:0xf bound_ctrl:1
	v_add_f32_dpp v166, v166, v166 row_half_mirror row_mask:0xf bank_mask:0xf bound_ctrl:1
	v_add_f32_dpp v169, v169, v169 row_half_mirror row_mask:0xf bank_mask:0xf bound_ctrl:1
	ds_read_b32 v41, v163 offset:13952
	v_add_f32_dpp v170, v170, v170 row_half_mirror row_mask:0xf bank_mask:0xf bound_ctrl:1
	s_waitcnt lgkmcnt(11)
	v_pk_fma_f32 v[148:149], v[86:87], v[94:95], v[148:149] op_sel:[0,1,0] op_sel_hi:[1,1,1]
	v_pk_fma_f32 v[150:151], v[88:89], v[94:95], v[150:151] op_sel:[0,1,0] op_sel_hi:[1,1,1]
	ds_read_b128 v[32:35], v174 offset:13440
	v_add_f32_dpp v168, v168, v168 quad_perm:[1,0,3,2] row_mask:0xf bank_mask:0xf bound_ctrl:1
	v_add_f32_dpp v166, v166, v166 quad_perm:[1,0,3,2] row_mask:0xf bank_mask:0xf bound_ctrl:1
	v_add_f32_dpp v169, v169, v169 quad_perm:[1,0,3,2] row_mask:0xf bank_mask:0xf bound_ctrl:1
	ds_read_b128 v[36:39], v175 offset:14208
	v_add_f32_dpp v170, v170, v170 quad_perm:[1,0,3,2] row_mask:0xf bank_mask:0xf bound_ctrl:1
	v_add_f32_dpp v168, v168, v168 quad_perm:[2,3,0,1] row_mask:0xf bank_mask:0xf bound_ctrl:1
	v_add_f32_dpp v166, v166, v166 quad_perm:[2,3,0,1] row_mask:0xf bank_mask:0xf bound_ctrl:1
	ds_read_b128 v[20:23], v174 offset:12672
	v_add_f32_dpp v169, v169, v169 quad_perm:[2,3,0,1] row_mask:0xf bank_mask:0xf bound_ctrl:1
	v_add_f32_dpp v170, v170, v170 quad_perm:[2,3,0,1] row_mask:0xf bank_mask:0xf bound_ctrl:1
	s_waitcnt lgkmcnt(13)
	v_fma_f32 v164, v94, v91, v169
	ds_read_b128 v[28:31], v174 offset:13184
	v_fma_f32 v171, v94, v93, v170
	s_waitcnt lgkmcnt(13)
	v_pk_fma_f32 v[148:149], v[74:75], v[166:167], v[148:149] op_sel_hi:[1,0,1]
	v_fma_f32 v167, v166, v90, v164
	ds_read_b128 v[16:19], v174 offset:12416
	v_pk_fma_f32 v[150:151], v[76:77], v[166:167], v[150:151] op_sel_hi:[1,0,1]
	v_fma_f32 v171, v166, v92, v171
	v_cndmask_b32_e64 v162, v162, v168, s[56:57]
	ds_read_b128 v[12:15], v174 offset:12160
	s_waitcnt lgkmcnt(14)
	v_pk_fma_f32 v[148:149], v[82:83], v[166:167], v[148:149] op_sel:[0,1,0] op_sel_hi:[1,1,1]
	v_pk_fma_f32 v[150:151], v[84:85], v[166:167], v[150:151] op_sel:[0,1,0] op_sel_hi:[1,1,1]
	v_cndmask_b32_e64 v162, v162, v171, s[58:59]
	s_waitcnt lgkmcnt(13)
	v_pk_fma_f32 v[144:145], v[144:145], v[70:71], v[148:149]
	v_pk_fma_f32 v[146:147], v[146:147], v[72:73], v[150:151]
	s_waitcnt lgkmcnt(9)
	v_pk_mul_f32 v[96:97], v[144:145], v[66:67]
	v_pk_mul_f32 v[98:99], v[144:145], v[0:1]
	v_pk_mul_f32 v[100:101], v[144:145], v[4:5]
	v_pk_mul_f32 v[172:173], v[144:145], v[8:9]
	v_pk_fma_f32 v[96:97], v[146:147], v[68:69], v[96:97]
	v_pk_fma_f32 v[98:99], v[146:147], v[2:3], v[98:99]
	ds_read_b128 v[54:57], v174 offset:14240
	v_pk_fma_f32 v[100:101], v[146:147], v[6:7], v[100:101]
	v_pk_fma_f32 v[172:173], v[146:147], v[10:11], v[172:173]
	v_add_f32_e32 v168, v96, v97
	ds_read_b128 v[58:61], v174 offset:14496
	v_add_f32_e32 v166, v98, v99
	v_add_f32_e32 v169, v100, v101
	v_add_f32_e32 v170, v172, v173
	ds_read_b128 v[62:65], v174 offset:14752
	v_add_f32_dpp v168, v168, v168 row_mirror row_mask:0xf bank_mask:0xf bound_ctrl:1
	v_add_f32_dpp v166, v166, v166 row_mirror row_mask:0xf bank_mask:0xf bound_ctrl:1
	v_add_f32_dpp v169, v169, v169 row_mirror row_mask:0xf bank_mask:0xf bound_ctrl:1
	ds_read_b128 v[78:81], v174 offset:15776
	v_add_f32_dpp v170, v170, v170 row_mirror row_mask:0xf bank_mask:0xf bound_ctrl:1
	s_waitcnt lgkmcnt(11)
	v_pk_mul_f32 v[148:149], v[24:25], v[40:41] op_sel_hi:[1,0]
	v_pk_mul_f32 v[150:151], v[26:27], v[40:41] op_sel_hi:[1,0]
	ds_read_b32 v94, v163 offset:16544
	v_add_f32_dpp v168, v168, v168 row_half_mirror row_mask:0xf bank_mask:0xf bound_ctrl:1
	v_add_f32_dpp v166, v166, v166 row_half_mirror row_mask:0xf bank_mask:0xf bound_ctrl:1
	v_add_f32_dpp v169, v169, v169 row_half_mirror row_mask:0xf bank_mask:0xf bound_ctrl:1
	ds_read_b32 v95, v163 offset:16800
	v_add_f32_dpp v170, v170, v170 row_half_mirror row_mask:0xf bank_mask:0xf bound_ctrl:1
	s_waitcnt lgkmcnt(11)
	v_pk_fma_f32 v[148:149], v[32:33], v[40:41], v[148:149] op_sel:[0,1,0] op_sel_hi:[1,1,1]
	v_pk_fma_f32 v[150:151], v[34:35], v[40:41], v[150:151] op_sel:[0,1,0] op_sel_hi:[1,1,1]
	ds_read_b128 v[86:89], v174 offset:16288
	v_add_f32_dpp v168, v168, v168 quad_perm:[1,0,3,2] row_mask:0xf bank_mask:0xf bound_ctrl:1
	v_add_f32_dpp v166, v166, v166 quad_perm:[1,0,3,2] row_mask:0xf bank_mask:0xf bound_ctrl:1
	v_add_f32_dpp v169, v169, v169 quad_perm:[1,0,3,2] row_mask:0xf bank_mask:0xf bound_ctrl:1
	ds_read_b128 v[90:93], v175 offset:17056
	v_add_f32_dpp v170, v170, v170 quad_perm:[1,0,3,2] row_mask:0xf bank_mask:0xf bound_ctrl:1
	v_add_f32_dpp v168, v168, v168 quad_perm:[2,3,0,1] row_mask:0xf bank_mask:0xf bound_ctrl:1
	v_add_f32_dpp v166, v166, v166 quad_perm:[2,3,0,1] row_mask:0xf bank_mask:0xf bound_ctrl:1
	ds_read_b128 v[74:77], v174 offset:15520
	v_add_f32_dpp v169, v169, v169 quad_perm:[2,3,0,1] row_mask:0xf bank_mask:0xf bound_ctrl:1
	v_add_f32_dpp v170, v170, v170 quad_perm:[2,3,0,1] row_mask:0xf bank_mask:0xf bound_ctrl:1
	s_waitcnt lgkmcnt(13)
	v_fma_f32 v164, v40, v37, v169
	ds_read_b128 v[82:85], v174 offset:16032
	v_fma_f32 v171, v40, v39, v170
	s_waitcnt lgkmcnt(13)
	v_pk_fma_f32 v[148:149], v[20:21], v[166:167], v[148:149] op_sel_hi:[1,0,1]
	v_fma_f32 v167, v166, v36, v164
	ds_read_b128 v[70:73], v174 offset:15264
	v_pk_fma_f32 v[150:151], v[22:23], v[166:167], v[150:151] op_sel_hi:[1,0,1]
	v_fma_f32 v171, v166, v38, v171
	v_cndmask_b32_e64 v162, v162, v168, s[60:61]
	ds_read_b128 v[66:69], v174 offset:15008
	s_waitcnt lgkmcnt(14)
	v_pk_fma_f32 v[148:149], v[28:29], v[166:167], v[148:149] op_sel:[0,1,0] op_sel_hi:[1,1,1]
	v_pk_fma_f32 v[150:151], v[30:31], v[166:167], v[150:151] op_sel:[0,1,0] op_sel_hi:[1,1,1]
	v_cndmask_b32_e64 v162, v162, v171, s[62:63]
	s_waitcnt lgkmcnt(13)
	v_pk_fma_f32 v[144:145], v[144:145], v[16:17], v[148:149]
	v_pk_fma_f32 v[146:147], v[146:147], v[18:19], v[150:151]
	s_waitcnt lgkmcnt(9)
	v_pk_mul_f32 v[96:97], v[144:145], v[12:13]
	v_pk_mul_f32 v[98:99], v[144:145], v[54:55]
	v_pk_mul_f32 v[100:101], v[144:145], v[58:59]
	v_pk_mul_f32 v[172:173], v[144:145], v[62:63]
	v_pk_fma_f32 v[96:97], v[146:147], v[14:15], v[96:97]
	v_pk_fma_f32 v[98:99], v[146:147], v[56:57], v[98:99]
	ds_read_b128 v[0:3], v174 offset:17088
	v_pk_fma_f32 v[100:101], v[146:147], v[60:61], v[100:101]
	v_pk_fma_f32 v[172:173], v[146:147], v[64:65], v[172:173]
	v_add_f32_e32 v168, v96, v97
	ds_read_b128 v[4:7], v174 offset:17344
	v_add_f32_e32 v166, v98, v99
	v_add_f32_e32 v169, v100, v101
	v_add_f32_e32 v170, v172, v173
	ds_read_b128 v[8:11], v174 offset:17600
	v_add_f32_dpp v168, v168, v168 row_mirror row_mask:0xf bank_mask:0xf bound_ctrl:1
	v_add_f32_dpp v166, v166, v166 row_mirror row_mask:0xf bank_mask:0xf bound_ctrl:1
	v_add_f32_dpp v169, v169, v169 row_mirror row_mask:0xf bank_mask:0xf bound_ctrl:1
	ds_read_b128 v[24:27], v174 offset:18624
	v_add_f32_dpp v170, v170, v170 row_mirror row_mask:0xf bank_mask:0xf bound_ctrl:1
	s_waitcnt lgkmcnt(11)
	v_pk_mul_f32 v[148:149], v[78:79], v[94:95] op_sel_hi:[1,0]
	v_pk_mul_f32 v[150:151], v[80:81], v[94:95] op_sel_hi:[1,0]
	ds_read_b32 v40, v163 offset:19392
	v_add_f32_dpp v168, v168, v168 row_half_mirror row_mask:0xf bank_mask:0xf bound_ctrl:1
	v_add_f32_dpp v166, v166, v166 row_half_mirror row_mask:0xf bank_mask:0xf bound_ctrl:1
	v_add_f32_dpp v169, v169, v169 row_half_mirror row_mask:0xf bank_mask:0xf bound_ctrl:1
	ds_read_b32 v41, v163 offset:19648
	v_add_f32_dpp v170, v170, v170 row_half_mirror row_mask:0xf bank_mask:0xf bound_ctrl:1
	s_waitcnt lgkmcnt(11)
	v_pk_fma_f32 v[148:149], v[86:87], v[94:95], v[148:149] op_sel:[0,1,0] op_sel_hi:[1,1,1]
	v_pk_fma_f32 v[150:151], v[88:89], v[94:95], v[150:151] op_sel:[0,1,0] op_sel_hi:[1,1,1]
	ds_read_b128 v[32:35], v174 offset:19136
	v_add_f32_dpp v168, v168, v168 quad_perm:[1,0,3,2] row_mask:0xf bank_mask:0xf bound_ctrl:1
	v_add_f32_dpp v166, v166, v166 quad_perm:[1,0,3,2] row_mask:0xf bank_mask:0xf bound_ctrl:1
	v_add_f32_dpp v169, v169, v169 quad_perm:[1,0,3,2] row_mask:0xf bank_mask:0xf bound_ctrl:1
	ds_read_b128 v[36:39], v175 offset:19904
	v_add_f32_dpp v170, v170, v170 quad_perm:[1,0,3,2] row_mask:0xf bank_mask:0xf bound_ctrl:1
	v_add_f32_dpp v168, v168, v168 quad_perm:[2,3,0,1] row_mask:0xf bank_mask:0xf bound_ctrl:1
	v_add_f32_dpp v166, v166, v166 quad_perm:[2,3,0,1] row_mask:0xf bank_mask:0xf bound_ctrl:1
	ds_read_b128 v[20:23], v174 offset:18368
	v_add_f32_dpp v169, v169, v169 quad_perm:[2,3,0,1] row_mask:0xf bank_mask:0xf bound_ctrl:1
	v_add_f32_dpp v170, v170, v170 quad_perm:[2,3,0,1] row_mask:0xf bank_mask:0xf bound_ctrl:1
	s_waitcnt lgkmcnt(13)
	v_fma_f32 v164, v94, v91, v169
	ds_read_b128 v[28:31], v174 offset:18880
	v_fma_f32 v171, v94, v93, v170
	s_waitcnt lgkmcnt(13)
	v_pk_fma_f32 v[148:149], v[74:75], v[166:167], v[148:149] op_sel_hi:[1,0,1]
	v_fma_f32 v167, v166, v90, v164
	ds_read_b128 v[16:19], v174 offset:18112
	v_pk_fma_f32 v[150:151], v[76:77], v[166:167], v[150:151] op_sel_hi:[1,0,1]
	v_fma_f32 v171, v166, v92, v171
	v_cndmask_b32_e64 v162, v162, v168, s[64:65]
	ds_read_b128 v[12:15], v174 offset:17856
	s_waitcnt lgkmcnt(14)
	v_pk_fma_f32 v[148:149], v[82:83], v[166:167], v[148:149] op_sel:[0,1,0] op_sel_hi:[1,1,1]
	v_pk_fma_f32 v[150:151], v[84:85], v[166:167], v[150:151] op_sel:[0,1,0] op_sel_hi:[1,1,1]
	v_cndmask_b32_e64 v162, v162, v171, s[66:67]
	s_waitcnt lgkmcnt(13)
	v_pk_fma_f32 v[144:145], v[144:145], v[70:71], v[148:149]
	v_pk_fma_f32 v[146:147], v[146:147], v[72:73], v[150:151]
	s_waitcnt lgkmcnt(9)
	v_pk_mul_f32 v[96:97], v[144:145], v[66:67]
	v_pk_mul_f32 v[98:99], v[144:145], v[0:1]
	v_pk_mul_f32 v[100:101], v[144:145], v[4:5]
	v_pk_mul_f32 v[172:173], v[144:145], v[8:9]
	v_pk_fma_f32 v[96:97], v[146:147], v[68:69], v[96:97]
	v_pk_fma_f32 v[98:99], v[146:147], v[2:3], v[98:99]
	ds_read_b128 v[54:57], v174 offset:19936
	v_pk_fma_f32 v[100:101], v[146:147], v[6:7], v[100:101]
	v_pk_fma_f32 v[172:173], v[146:147], v[10:11], v[172:173]
	v_add_f32_e32 v168, v96, v97
	ds_read_b128 v[58:61], v174 offset:20192
	v_add_f32_e32 v166, v98, v99
	v_add_f32_e32 v169, v100, v101
	v_add_f32_e32 v170, v172, v173
	ds_read_b128 v[62:65], v174 offset:20448
	v_add_f32_dpp v168, v168, v168 row_mirror row_mask:0xf bank_mask:0xf bound_ctrl:1
	v_add_f32_dpp v166, v166, v166 row_mirror row_mask:0xf bank_mask:0xf bound_ctrl:1
	v_add_f32_dpp v169, v169, v169 row_mirror row_mask:0xf bank_mask:0xf bound_ctrl:1
	ds_read_b128 v[78:81], v174 offset:21472
	v_add_f32_dpp v170, v170, v170 row_mirror row_mask:0xf bank_mask:0xf bound_ctrl:1
	s_waitcnt lgkmcnt(11)
	v_pk_mul_f32 v[148:149], v[24:25], v[40:41] op_sel_hi:[1,0]
	v_pk_mul_f32 v[150:151], v[26:27], v[40:41] op_sel_hi:[1,0]
	ds_read_b32 v94, v163 offset:22240
	v_add_f32_dpp v168, v168, v168 row_half_mirror row_mask:0xf bank_mask:0xf bound_ctrl:1
	v_add_f32_dpp v166, v166, v166 row_half_mirror row_mask:0xf bank_mask:0xf bound_ctrl:1
	v_add_f32_dpp v169, v169, v169 row_half_mirror row_mask:0xf bank_mask:0xf bound_ctrl:1
	ds_read_b32 v95, v163 offset:22496
	v_add_f32_dpp v170, v170, v170 row_half_mirror row_mask:0xf bank_mask:0xf bound_ctrl:1
	s_waitcnt lgkmcnt(11)
	v_pk_fma_f32 v[148:149], v[32:33], v[40:41], v[148:149] op_sel:[0,1,0] op_sel_hi:[1,1,1]
	v_pk_fma_f32 v[150:151], v[34:35], v[40:41], v[150:151] op_sel:[0,1,0] op_sel_hi:[1,1,1]
	ds_read_b128 v[86:89], v174 offset:21984
	v_add_f32_dpp v168, v168, v168 quad_perm:[1,0,3,2] row_mask:0xf bank_mask:0xf bound_ctrl:1
	v_add_f32_dpp v166, v166, v166 quad_perm:[1,0,3,2] row_mask:0xf bank_mask:0xf bound_ctrl:1
	v_add_f32_dpp v169, v169, v169 quad_perm:[1,0,3,2] row_mask:0xf bank_mask:0xf bound_ctrl:1
	ds_read_b128 v[90:93], v175 offset:22752
	v_add_f32_dpp v170, v170, v170 quad_perm:[1,0,3,2] row_mask:0xf bank_mask:0xf bound_ctrl:1
	v_add_f32_dpp v168, v168, v168 quad_perm:[2,3,0,1] row_mask:0xf bank_mask:0xf bound_ctrl:1
	v_add_f32_dpp v166, v166, v166 quad_perm:[2,3,0,1] row_mask:0xf bank_mask:0xf bound_ctrl:1
	ds_read_b128 v[74:77], v174 offset:21216
	v_add_f32_dpp v169, v169, v169 quad_perm:[2,3,0,1] row_mask:0xf bank_mask:0xf bound_ctrl:1
	v_add_f32_dpp v170, v170, v170 quad_perm:[2,3,0,1] row_mask:0xf bank_mask:0xf bound_ctrl:1
	s_waitcnt lgkmcnt(13)
	v_fma_f32 v164, v40, v37, v169
	ds_read_b128 v[82:85], v174 offset:21728
	v_fma_f32 v171, v40, v39, v170
	s_waitcnt lgkmcnt(13)
	v_pk_fma_f32 v[148:149], v[20:21], v[166:167], v[148:149] op_sel_hi:[1,0,1]
	v_fma_f32 v167, v166, v36, v164
	ds_read_b128 v[70:73], v174 offset:20960
	v_pk_fma_f32 v[150:151], v[22:23], v[166:167], v[150:151] op_sel_hi:[1,0,1]
	v_fma_f32 v171, v166, v38, v171
	v_cndmask_b32_e64 v162, v162, v168, s[68:69]
	ds_read_b128 v[66:69], v174 offset:20704
	s_waitcnt lgkmcnt(14)
	v_pk_fma_f32 v[148:149], v[28:29], v[166:167], v[148:149] op_sel:[0,1,0] op_sel_hi:[1,1,1]
	v_pk_fma_f32 v[150:151], v[30:31], v[166:167], v[150:151] op_sel:[0,1,0] op_sel_hi:[1,1,1]
	v_cndmask_b32_e64 v162, v162, v171, s[70:71]
	s_waitcnt lgkmcnt(13)
	v_pk_fma_f32 v[144:145], v[144:145], v[16:17], v[148:149]
	v_pk_fma_f32 v[146:147], v[146:147], v[18:19], v[150:151]
	s_waitcnt lgkmcnt(9)
	v_pk_mul_f32 v[96:97], v[144:145], v[12:13]
	v_pk_mul_f32 v[98:99], v[144:145], v[54:55]
	v_pk_mul_f32 v[100:101], v[144:145], v[58:59]
	v_pk_mul_f32 v[172:173], v[144:145], v[62:63]
	v_pk_fma_f32 v[96:97], v[146:147], v[14:15], v[96:97]
	v_pk_fma_f32 v[98:99], v[146:147], v[56:57], v[98:99]
	ds_read_b128 v[0:3], v174 offset:22784
	v_pk_fma_f32 v[100:101], v[146:147], v[60:61], v[100:101]
	v_pk_fma_f32 v[172:173], v[146:147], v[64:65], v[172:173]
	v_add_f32_e32 v168, v96, v97
	ds_read_b128 v[4:7], v174 offset:23040
	v_add_f32_e32 v166, v98, v99
	v_add_f32_e32 v169, v100, v101
	v_add_f32_e32 v170, v172, v173
	ds_read_b128 v[8:11], v174 offset:23296
	v_add_f32_dpp v168, v168, v168 row_mirror row_mask:0xf bank_mask:0xf bound_ctrl:1
	v_add_f32_dpp v166, v166, v166 row_mirror row_mask:0xf bank_mask:0xf bound_ctrl:1
	v_add_f32_dpp v169, v169, v169 row_mirror row_mask:0xf bank_mask:0xf bound_ctrl:1
	ds_read_b128 v[24:27], v174 offset:24320
	v_add_f32_dpp v170, v170, v170 row_mirror row_mask:0xf bank_mask:0xf bound_ctrl:1
	s_waitcnt lgkmcnt(11)
	v_pk_mul_f32 v[148:149], v[78:79], v[94:95] op_sel_hi:[1,0]
	v_pk_mul_f32 v[150:151], v[80:81], v[94:95] op_sel_hi:[1,0]
	ds_read_b32 v40, v163 offset:25088
	v_add_f32_dpp v168, v168, v168 row_half_mirror row_mask:0xf bank_mask:0xf bound_ctrl:1
	v_add_f32_dpp v166, v166, v166 row_half_mirror row_mask:0xf bank_mask:0xf bound_ctrl:1
	v_add_f32_dpp v169, v169, v169 row_half_mirror row_mask:0xf bank_mask:0xf bound_ctrl:1
	ds_read_b32 v41, v163 offset:25344
	v_add_f32_dpp v170, v170, v170 row_half_mirror row_mask:0xf bank_mask:0xf bound_ctrl:1
	s_waitcnt lgkmcnt(11)
	v_pk_fma_f32 v[148:149], v[86:87], v[94:95], v[148:149] op_sel:[0,1,0] op_sel_hi:[1,1,1]
	v_pk_fma_f32 v[150:151], v[88:89], v[94:95], v[150:151] op_sel:[0,1,0] op_sel_hi:[1,1,1]
	ds_read_b128 v[32:35], v174 offset:24832
	v_add_f32_dpp v168, v168, v168 quad_perm:[1,0,3,2] row_mask:0xf bank_mask:0xf bound_ctrl:1
	v_add_f32_dpp v166, v166, v166 quad_perm:[1,0,3,2] row_mask:0xf bank_mask:0xf bound_ctrl:1
	v_add_f32_dpp v169, v169, v169 quad_perm:[1,0,3,2] row_mask:0xf bank_mask:0xf bound_ctrl:1
	ds_read_b128 v[36:39], v175 offset:25600
	v_add_f32_dpp v170, v170, v170 quad_perm:[1,0,3,2] row_mask:0xf bank_mask:0xf bound_ctrl:1
	v_add_f32_dpp v168, v168, v168 quad_perm:[2,3,0,1] row_mask:0xf bank_mask:0xf bound_ctrl:1
	v_add_f32_dpp v166, v166, v166 quad_perm:[2,3,0,1] row_mask:0xf bank_mask:0xf bound_ctrl:1
	ds_read_b128 v[20:23], v174 offset:24064
	v_add_f32_dpp v169, v169, v169 quad_perm:[2,3,0,1] row_mask:0xf bank_mask:0xf bound_ctrl:1
	v_add_f32_dpp v170, v170, v170 quad_perm:[2,3,0,1] row_mask:0xf bank_mask:0xf bound_ctrl:1
	s_waitcnt lgkmcnt(13)
	v_fma_f32 v164, v94, v91, v169
	ds_read_b128 v[28:31], v174 offset:24576
	v_fma_f32 v171, v94, v93, v170
	s_waitcnt lgkmcnt(13)
	v_pk_fma_f32 v[148:149], v[74:75], v[166:167], v[148:149] op_sel_hi:[1,0,1]
	v_fma_f32 v167, v166, v90, v164
	ds_read_b128 v[16:19], v174 offset:23808
	v_pk_fma_f32 v[150:151], v[76:77], v[166:167], v[150:151] op_sel_hi:[1,0,1]
	v_fma_f32 v171, v166, v92, v171
	v_cndmask_b32_e64 v162, v162, v168, s[44:45]
	ds_read_b128 v[12:15], v174 offset:23552
	s_waitcnt lgkmcnt(14)
	v_pk_fma_f32 v[148:149], v[82:83], v[166:167], v[148:149] op_sel:[0,1,0] op_sel_hi:[1,1,1]
	v_pk_fma_f32 v[150:151], v[84:85], v[166:167], v[150:151] op_sel:[0,1,0] op_sel_hi:[1,1,1]
	v_cndmask_b32_e64 v162, v162, v171, s[42:43]
	s_waitcnt lgkmcnt(13)
	v_pk_fma_f32 v[144:145], v[144:145], v[70:71], v[148:149]
	v_pk_fma_f32 v[146:147], v[146:147], v[72:73], v[150:151]
	s_waitcnt lgkmcnt(9)
	v_pk_mul_f32 v[96:97], v[144:145], v[66:67]
	v_pk_mul_f32 v[98:99], v[144:145], v[0:1]
	v_pk_mul_f32 v[100:101], v[144:145], v[4:5]
	v_pk_mul_f32 v[172:173], v[144:145], v[8:9]
	v_pk_fma_f32 v[96:97], v[146:147], v[68:69], v[96:97]
	v_pk_fma_f32 v[98:99], v[146:147], v[2:3], v[98:99]
	ds_read_b128 v[54:57], v174 offset:25632
	v_pk_fma_f32 v[100:101], v[146:147], v[6:7], v[100:101]
	v_pk_fma_f32 v[172:173], v[146:147], v[10:11], v[172:173]
	v_add_f32_e32 v168, v96, v97
	ds_read_b128 v[58:61], v174 offset:25888
	v_add_f32_e32 v166, v98, v99
	v_add_f32_e32 v169, v100, v101
	v_add_f32_e32 v170, v172, v173
	ds_read_b128 v[62:65], v174 offset:26144
	v_add_f32_dpp v168, v168, v168 row_mirror row_mask:0xf bank_mask:0xf bound_ctrl:1
	v_add_f32_dpp v166, v166, v166 row_mirror row_mask:0xf bank_mask:0xf bound_ctrl:1
	v_add_f32_dpp v169, v169, v169 row_mirror row_mask:0xf bank_mask:0xf bound_ctrl:1
	ds_read_b128 v[78:81], v174 offset:27168
	v_add_f32_dpp v170, v170, v170 row_mirror row_mask:0xf bank_mask:0xf bound_ctrl:1
	s_waitcnt lgkmcnt(11)
	v_pk_mul_f32 v[148:149], v[24:25], v[40:41] op_sel_hi:[1,0]
	v_pk_mul_f32 v[150:151], v[26:27], v[40:41] op_sel_hi:[1,0]
	ds_read_b32 v94, v163 offset:27936
	v_add_f32_dpp v168, v168, v168 row_half_mirror row_mask:0xf bank_mask:0xf bound_ctrl:1
	v_add_f32_dpp v166, v166, v166 row_half_mirror row_mask:0xf bank_mask:0xf bound_ctrl:1
	v_add_f32_dpp v169, v169, v169 row_half_mirror row_mask:0xf bank_mask:0xf bound_ctrl:1
	ds_read_b32 v95, v163 offset:28192
	v_add_f32_dpp v170, v170, v170 row_half_mirror row_mask:0xf bank_mask:0xf bound_ctrl:1
	s_waitcnt lgkmcnt(11)
	v_pk_fma_f32 v[148:149], v[32:33], v[40:41], v[148:149] op_sel:[0,1,0] op_sel_hi:[1,1,1]
	v_pk_fma_f32 v[150:151], v[34:35], v[40:41], v[150:151] op_sel:[0,1,0] op_sel_hi:[1,1,1]
	ds_read_b128 v[86:89], v174 offset:27680
	v_add_f32_dpp v168, v168, v168 quad_perm:[1,0,3,2] row_mask:0xf bank_mask:0xf bound_ctrl:1
	v_add_f32_dpp v166, v166, v166 quad_perm:[1,0,3,2] row_mask:0xf bank_mask:0xf bound_ctrl:1
	v_add_f32_dpp v169, v169, v169 quad_perm:[1,0,3,2] row_mask:0xf bank_mask:0xf bound_ctrl:1
	ds_read_b128 v[90:93], v175 offset:28448
	v_add_f32_dpp v170, v170, v170 quad_perm:[1,0,3,2] row_mask:0xf bank_mask:0xf bound_ctrl:1
	v_add_f32_dpp v168, v168, v168 quad_perm:[2,3,0,1] row_mask:0xf bank_mask:0xf bound_ctrl:1
	v_add_f32_dpp v166, v166, v166 quad_perm:[2,3,0,1] row_mask:0xf bank_mask:0xf bound_ctrl:1
	ds_read_b128 v[74:77], v174 offset:26912
	v_add_f32_dpp v169, v169, v169 quad_perm:[2,3,0,1] row_mask:0xf bank_mask:0xf bound_ctrl:1
	v_add_f32_dpp v170, v170, v170 quad_perm:[2,3,0,1] row_mask:0xf bank_mask:0xf bound_ctrl:1
	s_waitcnt lgkmcnt(13)
	v_fma_f32 v164, v40, v37, v169
	ds_read_b128 v[82:85], v174 offset:27424
	v_fma_f32 v171, v40, v39, v170
	s_waitcnt lgkmcnt(13)
	v_pk_fma_f32 v[148:149], v[20:21], v[166:167], v[148:149] op_sel_hi:[1,0,1]
	v_fma_f32 v167, v166, v36, v164
	ds_read_b128 v[70:73], v174 offset:26656
	v_pk_fma_f32 v[150:151], v[22:23], v[166:167], v[150:151] op_sel_hi:[1,0,1]
	v_fma_f32 v171, v166, v38, v171
	v_cndmask_b32_e64 v162, v162, v168, s[46:47]
	ds_read_b128 v[66:69], v174 offset:26400
	s_lshl_b32 s6, s9, 1
	s_add_i32 s6, s6, 1
	s_add_i32 s6, s6, -1
	s_and_b32 s6, s6, 7
	s_lshl_b32 s6, s6, 10
	v_add_u32_e32 v161, s6, v156
	ds_write_b32 v161, v162
	s_waitcnt lgkmcnt(15)
	v_pk_fma_f32 v[148:149], v[28:29], v[166:167], v[148:149] op_sel:[0,1,0] op_sel_hi:[1,1,1]
	v_pk_fma_f32 v[150:151], v[30:31], v[166:167], v[150:151] op_sel:[0,1,0] op_sel_hi:[1,1,1]
	v_cndmask_b32_e64 v162, v162, v171, s[38:39]
	s_waitcnt lgkmcnt(14)
	v_pk_fma_f32 v[144:145], v[144:145], v[16:17], v[148:149]
	v_pk_fma_f32 v[146:147], v[146:147], v[18:19], v[150:151]
	s_waitcnt lgkmcnt(10)
	v_pk_mul_f32 v[96:97], v[144:145], v[12:13]
	v_pk_mul_f32 v[98:99], v[144:145], v[54:55]
	v_pk_mul_f32 v[100:101], v[144:145], v[58:59]
	v_pk_mul_f32 v[172:173], v[144:145], v[62:63]
	v_pk_fma_f32 v[96:97], v[146:147], v[14:15], v[96:97]
	v_pk_fma_f32 v[98:99], v[146:147], v[56:57], v[98:99]
	ds_read_b128 v[0:3], v174 offset:28480
	v_pk_fma_f32 v[100:101], v[146:147], v[60:61], v[100:101]
	v_pk_fma_f32 v[172:173], v[146:147], v[64:65], v[172:173]
	v_add_f32_e32 v168, v96, v97
	ds_read_b128 v[4:7], v174 offset:28736
	v_add_f32_e32 v166, v98, v99
	v_add_f32_e32 v169, v100, v101
	v_add_f32_e32 v170, v172, v173
	ds_read_b128 v[8:11], v174 offset:28992
	v_add_f32_dpp v168, v168, v168 row_mirror row_mask:0xf bank_mask:0xf bound_ctrl:1
	v_add_f32_dpp v166, v166, v166 row_mirror row_mask:0xf bank_mask:0xf bound_ctrl:1
	v_add_f32_dpp v169, v169, v169 row_mirror row_mask:0xf bank_mask:0xf bound_ctrl:1
	ds_read_b128 v[24:27], v174 offset:30016
	v_add_f32_dpp v170, v170, v170 row_mirror row_mask:0xf bank_mask:0xf bound_ctrl:1
	s_waitcnt lgkmcnt(12)
	v_pk_mul_f32 v[148:149], v[78:79], v[94:95] op_sel_hi:[1,0]
	v_pk_mul_f32 v[150:151], v[80:81], v[94:95] op_sel_hi:[1,0]
	ds_read_b32 v40, v163 offset:30784
	v_add_f32_dpp v168, v168, v168 row_half_mirror row_mask:0xf bank_mask:0xf bound_ctrl:1
	v_add_f32_dpp v166, v166, v166 row_half_mirror row_mask:0xf bank_mask:0xf bound_ctrl:1
	v_add_f32_dpp v169, v169, v169 row_half_mirror row_mask:0xf bank_mask:0xf bound_ctrl:1
	ds_read_b32 v41, v163 offset:31040
	v_add_f32_dpp v170, v170, v170 row_half_mirror row_mask:0xf bank_mask:0xf bound_ctrl:1
	s_waitcnt lgkmcnt(12)
	v_pk_fma_f32 v[148:149], v[86:87], v[94:95], v[148:149] op_sel:[0,1,0] op_sel_hi:[1,1,1]
	v_pk_fma_f32 v[150:151], v[88:89], v[94:95], v[150:151] op_sel:[0,1,0] op_sel_hi:[1,1,1]
	ds_read_b128 v[32:35], v174 offset:30528
	v_add_f32_dpp v168, v168, v168 quad_perm:[1,0,3,2] row_mask:0xf bank_mask:0xf bound_ctrl:1
	v_add_f32_dpp v166, v166, v166 quad_perm:[1,0,3,2] row_mask:0xf bank_mask:0xf bound_ctrl:1
	v_add_f32_dpp v169, v169, v169 quad_perm:[1,0,3,2] row_mask:0xf bank_mask:0xf bound_ctrl:1
	ds_read_b128 v[36:39], v175 offset:31296
	v_add_f32_dpp v170, v170, v170 quad_perm:[1,0,3,2] row_mask:0xf bank_mask:0xf bound_ctrl:1
	v_add_f32_dpp v168, v168, v168 quad_perm:[2,3,0,1] row_mask:0xf bank_mask:0xf bound_ctrl:1
	v_add_f32_dpp v166, v166, v166 quad_perm:[2,3,0,1] row_mask:0xf bank_mask:0xf bound_ctrl:1
	ds_read_b128 v[20:23], v174 offset:29760
	v_add_f32_dpp v169, v169, v169 quad_perm:[2,3,0,1] row_mask:0xf bank_mask:0xf bound_ctrl:1
	v_add_f32_dpp v170, v170, v170 quad_perm:[2,3,0,1] row_mask:0xf bank_mask:0xf bound_ctrl:1
	s_waitcnt lgkmcnt(14)
	v_fma_f32 v164, v94, v91, v169
	ds_read_b128 v[28:31], v174 offset:30272
	v_fma_f32 v171, v94, v93, v170
	s_waitcnt lgkmcnt(14)
	v_pk_fma_f32 v[148:149], v[74:75], v[166:167], v[148:149] op_sel_hi:[1,0,1]
	v_fma_f32 v167, v166, v90, v164
	ds_read_b128 v[16:19], v174 offset:29504
	v_pk_fma_f32 v[150:151], v[76:77], v[166:167], v[150:151] op_sel_hi:[1,0,1]
	v_fma_f32 v171, v166, v92, v171
	v_cndmask_b32_e64 v162, v162, v168, s[48:49]
	ds_read_b128 v[12:15], v174 offset:29248
	s_waitcnt lgkmcnt(15)
	v_pk_fma_f32 v[148:149], v[82:83], v[166:167], v[148:149] op_sel:[0,1,0] op_sel_hi:[1,1,1]
	v_pk_fma_f32 v[150:151], v[84:85], v[166:167], v[150:151] op_sel:[0,1,0] op_sel_hi:[1,1,1]
	v_cndmask_b32_e64 v162, v162, v171, s[50:51]
	s_waitcnt lgkmcnt(14)
	v_pk_fma_f32 v[144:145], v[144:145], v[70:71], v[148:149]
	v_pk_fma_f32 v[146:147], v[146:147], v[72:73], v[150:151]
	s_waitcnt lgkmcnt(9)
	v_pk_mul_f32 v[96:97], v[144:145], v[66:67]
	v_pk_mul_f32 v[98:99], v[144:145], v[0:1]
	v_pk_mul_f32 v[100:101], v[144:145], v[4:5]
	v_pk_mul_f32 v[172:173], v[144:145], v[8:9]
	v_pk_fma_f32 v[96:97], v[146:147], v[68:69], v[96:97]
	v_pk_fma_f32 v[98:99], v[146:147], v[2:3], v[98:99]
	ds_read_b128 v[54:57], v174 offset:31328
	v_pk_fma_f32 v[100:101], v[146:147], v[6:7], v[100:101]
	v_pk_fma_f32 v[172:173], v[146:147], v[10:11], v[172:173]
	v_add_f32_e32 v168, v96, v97
	ds_read_b128 v[58:61], v174 offset:31584
	v_add_f32_e32 v166, v98, v99
	v_add_f32_e32 v169, v100, v101
	v_add_f32_e32 v170, v172, v173
	ds_read_b128 v[62:65], v174 offset:31840
	v_add_f32_dpp v168, v168, v168 row_mirror row_mask:0xf bank_mask:0xf bound_ctrl:1
	v_add_f32_dpp v166, v166, v166 row_mirror row_mask:0xf bank_mask:0xf bound_ctrl:1
	v_add_f32_dpp v169, v169, v169 row_mirror row_mask:0xf bank_mask:0xf bound_ctrl:1
	ds_read_b128 v[78:81], v174 offset:32864
	v_add_f32_dpp v170, v170, v170 row_mirror row_mask:0xf bank_mask:0xf bound_ctrl:1
	s_waitcnt lgkmcnt(11)
	v_pk_mul_f32 v[148:149], v[24:25], v[40:41] op_sel_hi:[1,0]
	v_pk_mul_f32 v[150:151], v[26:27], v[40:41] op_sel_hi:[1,0]
	ds_read_b32 v94, v163 offset:33632
	v_add_f32_dpp v168, v168, v168 row_half_mirror row_mask:0xf bank_mask:0xf bound_ctrl:1
	v_add_f32_dpp v166, v166, v166 row_half_mirror row_mask:0xf bank_mask:0xf bound_ctrl:1
	v_add_f32_dpp v169, v169, v169 row_half_mirror row_mask:0xf bank_mask:0xf bound_ctrl:1
	ds_read_b32 v95, v163 offset:33888
	v_add_f32_dpp v170, v170, v170 row_half_mirror row_mask:0xf bank_mask:0xf bound_ctrl:1
	s_waitcnt lgkmcnt(11)
	v_pk_fma_f32 v[148:149], v[32:33], v[40:41], v[148:149] op_sel:[0,1,0] op_sel_hi:[1,1,1]
	v_pk_fma_f32 v[150:151], v[34:35], v[40:41], v[150:151] op_sel:[0,1,0] op_sel_hi:[1,1,1]
	ds_read_b128 v[86:89], v174 offset:33376
	v_add_f32_dpp v168, v168, v168 quad_perm:[1,0,3,2] row_mask:0xf bank_mask:0xf bound_ctrl:1
	v_add_f32_dpp v166, v166, v166 quad_perm:[1,0,3,2] row_mask:0xf bank_mask:0xf bound_ctrl:1
	v_add_f32_dpp v169, v169, v169 quad_perm:[1,0,3,2] row_mask:0xf bank_mask:0xf bound_ctrl:1
	ds_read_b128 v[90:93], v175 offset:34144
	v_add_f32_dpp v170, v170, v170 quad_perm:[1,0,3,2] row_mask:0xf bank_mask:0xf bound_ctrl:1
	v_add_f32_dpp v168, v168, v168 quad_perm:[2,3,0,1] row_mask:0xf bank_mask:0xf bound_ctrl:1
	v_add_f32_dpp v166, v166, v166 quad_perm:[2,3,0,1] row_mask:0xf bank_mask:0xf bound_ctrl:1
	ds_read_b128 v[74:77], v174 offset:32608
	v_add_f32_dpp v169, v169, v169 quad_perm:[2,3,0,1] row_mask:0xf bank_mask:0xf bound_ctrl:1
	v_add_f32_dpp v170, v170, v170 quad_perm:[2,3,0,1] row_mask:0xf bank_mask:0xf bound_ctrl:1
	s_waitcnt lgkmcnt(13)
	v_fma_f32 v164, v40, v37, v169
	ds_read_b128 v[82:85], v174 offset:33120
	v_fma_f32 v171, v40, v39, v170
	s_waitcnt lgkmcnt(13)
	v_pk_fma_f32 v[148:149], v[20:21], v[166:167], v[148:149] op_sel_hi:[1,0,1]
	v_fma_f32 v167, v166, v36, v164
	ds_read_b128 v[70:73], v174 offset:32352
	v_pk_fma_f32 v[150:151], v[22:23], v[166:167], v[150:151] op_sel_hi:[1,0,1]
	v_fma_f32 v171, v166, v38, v171
	v_cndmask_b32_e64 v162, v162, v168, s[52:53]
	ds_read_b128 v[66:69], v174 offset:32096
	s_waitcnt lgkmcnt(14)
	v_pk_fma_f32 v[148:149], v[28:29], v[166:167], v[148:149] op_sel:[0,1,0] op_sel_hi:[1,1,1]
	v_pk_fma_f32 v[150:151], v[30:31], v[166:167], v[150:151] op_sel:[0,1,0] op_sel_hi:[1,1,1]
	v_cndmask_b32_e64 v162, v162, v171, s[54:55]
	s_waitcnt lgkmcnt(13)
	v_pk_fma_f32 v[144:145], v[144:145], v[16:17], v[148:149]
	v_pk_fma_f32 v[146:147], v[146:147], v[18:19], v[150:151]
	s_waitcnt lgkmcnt(9)
	v_pk_mul_f32 v[96:97], v[144:145], v[12:13]
	v_pk_mul_f32 v[98:99], v[144:145], v[54:55]
	v_pk_mul_f32 v[100:101], v[144:145], v[58:59]
	v_pk_mul_f32 v[172:173], v[144:145], v[62:63]
	v_pk_fma_f32 v[96:97], v[146:147], v[14:15], v[96:97]
	v_pk_fma_f32 v[98:99], v[146:147], v[56:57], v[98:99]
	ds_read_b128 v[0:3], v174 offset:34176
	v_pk_fma_f32 v[100:101], v[146:147], v[60:61], v[100:101]
	v_pk_fma_f32 v[172:173], v[146:147], v[64:65], v[172:173]
	v_add_f32_e32 v168, v96, v97
	ds_read_b128 v[4:7], v174 offset:34432
	v_add_f32_e32 v166, v98, v99
	v_add_f32_e32 v169, v100, v101
	v_add_f32_e32 v170, v172, v173
	ds_read_b128 v[8:11], v174 offset:34688
	v_add_f32_dpp v168, v168, v168 row_mirror row_mask:0xf bank_mask:0xf bound_ctrl:1
	v_add_f32_dpp v166, v166, v166 row_mirror row_mask:0xf bank_mask:0xf bound_ctrl:1
	v_add_f32_dpp v169, v169, v169 row_mirror row_mask:0xf bank_mask:0xf bound_ctrl:1
	ds_read_b128 v[24:27], v174 offset:35712
	v_add_f32_dpp v170, v170, v170 row_mirror row_mask:0xf bank_mask:0xf bound_ctrl:1
	s_waitcnt lgkmcnt(11)
	v_pk_mul_f32 v[148:149], v[78:79], v[94:95] op_sel_hi:[1,0]
	v_pk_mul_f32 v[150:151], v[80:81], v[94:95] op_sel_hi:[1,0]
	ds_read_b32 v40, v163 offset:36480
	v_add_f32_dpp v168, v168, v168 row_half_mirror row_mask:0xf bank_mask:0xf bound_ctrl:1
	v_add_f32_dpp v166, v166, v166 row_half_mirror row_mask:0xf bank_mask:0xf bound_ctrl:1
	v_add_f32_dpp v169, v169, v169 row_half_mirror row_mask:0xf bank_mask:0xf bound_ctrl:1
	ds_read_b32 v41, v163 offset:36736
	v_add_f32_dpp v170, v170, v170 row_half_mirror row_mask:0xf bank_mask:0xf bound_ctrl:1
	s_waitcnt lgkmcnt(11)
	v_pk_fma_f32 v[148:149], v[86:87], v[94:95], v[148:149] op_sel:[0,1,0] op_sel_hi:[1,1,1]
	v_pk_fma_f32 v[150:151], v[88:89], v[94:95], v[150:151] op_sel:[0,1,0] op_sel_hi:[1,1,1]
	ds_read_b128 v[32:35], v174 offset:36224
	v_add_f32_dpp v168, v168, v168 quad_perm:[1,0,3,2] row_mask:0xf bank_mask:0xf bound_ctrl:1
	v_add_f32_dpp v166, v166, v166 quad_perm:[1,0,3,2] row_mask:0xf bank_mask:0xf bound_ctrl:1
	v_add_f32_dpp v169, v169, v169 quad_perm:[1,0,3,2] row_mask:0xf bank_mask:0xf bound_ctrl:1
	ds_read_b128 v[36:39], v175 offset:36992
	v_add_f32_dpp v170, v170, v170 quad_perm:[1,0,3,2] row_mask:0xf bank_mask:0xf bound_ctrl:1
	v_add_f32_dpp v168, v168, v168 quad_perm:[2,3,0,1] row_mask:0xf bank_mask:0xf bound_ctrl:1
	v_add_f32_dpp v166, v166, v166 quad_perm:[2,3,0,1] row_mask:0xf bank_mask:0xf bound_ctrl:1
	ds_read_b128 v[20:23], v174 offset:35456
	v_add_f32_dpp v169, v169, v169 quad_perm:[2,3,0,1] row_mask:0xf bank_mask:0xf bound_ctrl:1
	v_add_f32_dpp v170, v170, v170 quad_perm:[2,3,0,1] row_mask:0xf bank_mask:0xf bound_ctrl:1
	s_waitcnt lgkmcnt(13)
	v_fma_f32 v164, v94, v91, v169
	ds_read_b128 v[28:31], v174 offset:35968
	v_fma_f32 v171, v94, v93, v170
	s_waitcnt lgkmcnt(13)
	v_pk_fma_f32 v[148:149], v[74:75], v[166:167], v[148:149] op_sel_hi:[1,0,1]
	v_fma_f32 v167, v166, v90, v164
	ds_read_b128 v[16:19], v174 offset:35200
	v_pk_fma_f32 v[150:151], v[76:77], v[166:167], v[150:151] op_sel_hi:[1,0,1]
	v_fma_f32 v171, v166, v92, v171
	v_cndmask_b32_e64 v162, v162, v168, s[56:57]
	ds_read_b128 v[12:15], v174 offset:34944
	s_waitcnt lgkmcnt(14)
	v_pk_fma_f32 v[148:149], v[82:83], v[166:167], v[148:149] op_sel:[0,1,0] op_sel_hi:[1,1,1]
	v_pk_fma_f32 v[150:151], v[84:85], v[166:167], v[150:151] op_sel:[0,1,0] op_sel_hi:[1,1,1]
	v_cndmask_b32_e64 v162, v162, v171, s[58:59]
	s_waitcnt lgkmcnt(13)
	v_pk_fma_f32 v[144:145], v[144:145], v[70:71], v[148:149]
	v_pk_fma_f32 v[146:147], v[146:147], v[72:73], v[150:151]
	s_waitcnt lgkmcnt(9)
	v_pk_mul_f32 v[96:97], v[144:145], v[66:67]
	v_pk_mul_f32 v[98:99], v[144:145], v[0:1]
	v_pk_mul_f32 v[100:101], v[144:145], v[4:5]
	v_pk_mul_f32 v[172:173], v[144:145], v[8:9]
	v_pk_fma_f32 v[96:97], v[146:147], v[68:69], v[96:97]
	v_pk_fma_f32 v[98:99], v[146:147], v[2:3], v[98:99]
	ds_read_b128 v[54:57], v174 offset:37024
	v_pk_fma_f32 v[100:101], v[146:147], v[6:7], v[100:101]
	v_pk_fma_f32 v[172:173], v[146:147], v[10:11], v[172:173]
	v_add_f32_e32 v168, v96, v97
	ds_read_b128 v[58:61], v174 offset:37280
	v_add_f32_e32 v166, v98, v99
	v_add_f32_e32 v169, v100, v101
	v_add_f32_e32 v170, v172, v173
	ds_read_b128 v[62:65], v174 offset:37536
	v_add_f32_dpp v168, v168, v168 row_mirror row_mask:0xf bank_mask:0xf bound_ctrl:1
	v_add_f32_dpp v166, v166, v166 row_mirror row_mask:0xf bank_mask:0xf bound_ctrl:1
	v_add_f32_dpp v169, v169, v169 row_mirror row_mask:0xf bank_mask:0xf bound_ctrl:1
	ds_read_b128 v[78:81], v174 offset:38560
	v_add_f32_dpp v170, v170, v170 row_mirror row_mask:0xf bank_mask:0xf bound_ctrl:1
	s_waitcnt lgkmcnt(11)
	v_pk_mul_f32 v[148:149], v[24:25], v[40:41] op_sel_hi:[1,0]
	v_pk_mul_f32 v[150:151], v[26:27], v[40:41] op_sel_hi:[1,0]
	ds_read_b32 v94, v163 offset:39328
	v_add_f32_dpp v168, v168, v168 row_half_mirror row_mask:0xf bank_mask:0xf bound_ctrl:1
	v_add_f32_dpp v166, v166, v166 row_half_mirror row_mask:0xf bank_mask:0xf bound_ctrl:1
	v_add_f32_dpp v169, v169, v169 row_half_mirror row_mask:0xf bank_mask:0xf bound_ctrl:1
	ds_read_b32 v95, v163 offset:39584
	v_add_f32_dpp v170, v170, v170 row_half_mirror row_mask:0xf bank_mask:0xf bound_ctrl:1
	s_waitcnt lgkmcnt(11)
	v_pk_fma_f32 v[148:149], v[32:33], v[40:41], v[148:149] op_sel:[0,1,0] op_sel_hi:[1,1,1]
	v_pk_fma_f32 v[150:151], v[34:35], v[40:41], v[150:151] op_sel:[0,1,0] op_sel_hi:[1,1,1]
	ds_read_b128 v[86:89], v174 offset:39072
	v_add_f32_dpp v168, v168, v168 quad_perm:[1,0,3,2] row_mask:0xf bank_mask:0xf bound_ctrl:1
	v_add_f32_dpp v166, v166, v166 quad_perm:[1,0,3,2] row_mask:0xf bank_mask:0xf bound_ctrl:1
	v_add_f32_dpp v169, v169, v169 quad_perm:[1,0,3,2] row_mask:0xf bank_mask:0xf bound_ctrl:1
	ds_read_b128 v[90:93], v175 offset:39840
	v_add_f32_dpp v170, v170, v170 quad_perm:[1,0,3,2] row_mask:0xf bank_mask:0xf bound_ctrl:1
	v_add_f32_dpp v168, v168, v168 quad_perm:[2,3,0,1] row_mask:0xf bank_mask:0xf bound_ctrl:1
	v_add_f32_dpp v166, v166, v166 quad_perm:[2,3,0,1] row_mask:0xf bank_mask:0xf bound_ctrl:1
	ds_read_b128 v[74:77], v174 offset:38304
	v_add_f32_dpp v169, v169, v169 quad_perm:[2,3,0,1] row_mask:0xf bank_mask:0xf bound_ctrl:1
	v_add_f32_dpp v170, v170, v170 quad_perm:[2,3,0,1] row_mask:0xf bank_mask:0xf bound_ctrl:1
	s_waitcnt lgkmcnt(13)
	v_fma_f32 v164, v40, v37, v169
	ds_read_b128 v[82:85], v174 offset:38816
	v_fma_f32 v171, v40, v39, v170
	s_waitcnt lgkmcnt(13)
	v_pk_fma_f32 v[148:149], v[20:21], v[166:167], v[148:149] op_sel_hi:[1,0,1]
	v_fma_f32 v167, v166, v36, v164
	ds_read_b128 v[70:73], v174 offset:38048
	v_pk_fma_f32 v[150:151], v[22:23], v[166:167], v[150:151] op_sel_hi:[1,0,1]
	v_fma_f32 v171, v166, v38, v171
	v_cndmask_b32_e64 v162, v162, v168, s[60:61]
	ds_read_b128 v[66:69], v174 offset:37792
	s_waitcnt lgkmcnt(14)
	v_pk_fma_f32 v[148:149], v[28:29], v[166:167], v[148:149] op_sel:[0,1,0] op_sel_hi:[1,1,1]
	v_pk_fma_f32 v[150:151], v[30:31], v[166:167], v[150:151] op_sel:[0,1,0] op_sel_hi:[1,1,1]
	v_cndmask_b32_e64 v162, v162, v171, s[62:63]
	s_waitcnt lgkmcnt(13)
	v_pk_fma_f32 v[144:145], v[144:145], v[16:17], v[148:149]
	v_pk_fma_f32 v[146:147], v[146:147], v[18:19], v[150:151]
	s_waitcnt lgkmcnt(9)
	v_pk_mul_f32 v[96:97], v[144:145], v[12:13]
	v_pk_mul_f32 v[98:99], v[144:145], v[54:55]
	v_pk_mul_f32 v[100:101], v[144:145], v[58:59]
	v_pk_mul_f32 v[172:173], v[144:145], v[62:63]
	v_pk_fma_f32 v[96:97], v[146:147], v[14:15], v[96:97]
	v_pk_fma_f32 v[98:99], v[146:147], v[56:57], v[98:99]
	ds_read_b128 v[0:3], v174 offset:39872
	v_pk_fma_f32 v[100:101], v[146:147], v[60:61], v[100:101]
	v_pk_fma_f32 v[172:173], v[146:147], v[64:65], v[172:173]
	v_add_f32_e32 v168, v96, v97
	ds_read_b128 v[4:7], v174 offset:40128
	v_add_f32_e32 v166, v98, v99
	v_add_f32_e32 v169, v100, v101
	v_add_f32_e32 v170, v172, v173
	ds_read_b128 v[8:11], v174 offset:40384
	v_add_f32_dpp v168, v168, v168 row_mirror row_mask:0xf bank_mask:0xf bound_ctrl:1
	v_add_f32_dpp v166, v166, v166 row_mirror row_mask:0xf bank_mask:0xf bound_ctrl:1
	v_add_f32_dpp v169, v169, v169 row_mirror row_mask:0xf bank_mask:0xf bound_ctrl:1
	ds_read_b128 v[24:27], v174 offset:41408
	v_add_f32_dpp v170, v170, v170 row_mirror row_mask:0xf bank_mask:0xf bound_ctrl:1
	s_waitcnt lgkmcnt(11)
	v_pk_mul_f32 v[148:149], v[78:79], v[94:95] op_sel_hi:[1,0]
	v_pk_mul_f32 v[150:151], v[80:81], v[94:95] op_sel_hi:[1,0]
	ds_read_b32 v40, v163 offset:42176
	v_add_f32_dpp v168, v168, v168 row_half_mirror row_mask:0xf bank_mask:0xf bound_ctrl:1
	v_add_f32_dpp v166, v166, v166 row_half_mirror row_mask:0xf bank_mask:0xf bound_ctrl:1
	v_add_f32_dpp v169, v169, v169 row_half_mirror row_mask:0xf bank_mask:0xf bound_ctrl:1
	ds_read_b32 v41, v163 offset:42432
	v_add_f32_dpp v170, v170, v170 row_half_mirror row_mask:0xf bank_mask:0xf bound_ctrl:1
	s_waitcnt lgkmcnt(11)
	v_pk_fma_f32 v[148:149], v[86:87], v[94:95], v[148:149] op_sel:[0,1,0] op_sel_hi:[1,1,1]
	v_pk_fma_f32 v[150:151], v[88:89], v[94:95], v[150:151] op_sel:[0,1,0] op_sel_hi:[1,1,1]
	ds_read_b128 v[32:35], v174 offset:41920
	v_add_f32_dpp v168, v168, v168 quad_perm:[1,0,3,2] row_mask:0xf bank_mask:0xf bound_ctrl:1
	v_add_f32_dpp v166, v166, v166 quad_perm:[1,0,3,2] row_mask:0xf bank_mask:0xf bound_ctrl:1
	v_add_f32_dpp v169, v169, v169 quad_perm:[1,0,3,2] row_mask:0xf bank_mask:0xf bound_ctrl:1
	ds_read_b128 v[36:39], v175 offset:42688
	v_add_f32_dpp v170, v170, v170 quad_perm:[1,0,3,2] row_mask:0xf bank_mask:0xf bound_ctrl:1
	v_add_f32_dpp v168, v168, v168 quad_perm:[2,3,0,1] row_mask:0xf bank_mask:0xf bound_ctrl:1
	v_add_f32_dpp v166, v166, v166 quad_perm:[2,3,0,1] row_mask:0xf bank_mask:0xf bound_ctrl:1
	ds_read_b128 v[20:23], v174 offset:41152
	v_add_f32_dpp v169, v169, v169 quad_perm:[2,3,0,1] row_mask:0xf bank_mask:0xf bound_ctrl:1
	v_add_f32_dpp v170, v170, v170 quad_perm:[2,3,0,1] row_mask:0xf bank_mask:0xf bound_ctrl:1
	s_waitcnt lgkmcnt(13)
	v_fma_f32 v164, v94, v91, v169
	ds_read_b128 v[28:31], v174 offset:41664
	v_fma_f32 v171, v94, v93, v170
	s_waitcnt lgkmcnt(13)
	v_pk_fma_f32 v[148:149], v[74:75], v[166:167], v[148:149] op_sel_hi:[1,0,1]
	v_fma_f32 v167, v166, v90, v164
	ds_read_b128 v[16:19], v174 offset:40896
	v_pk_fma_f32 v[150:151], v[76:77], v[166:167], v[150:151] op_sel_hi:[1,0,1]
	v_fma_f32 v171, v166, v92, v171
	v_cndmask_b32_e64 v162, v162, v168, s[64:65]
	ds_read_b128 v[12:15], v174 offset:40640
	s_waitcnt lgkmcnt(14)
	v_pk_fma_f32 v[148:149], v[82:83], v[166:167], v[148:149] op_sel:[0,1,0] op_sel_hi:[1,1,1]
	v_pk_fma_f32 v[150:151], v[84:85], v[166:167], v[150:151] op_sel:[0,1,0] op_sel_hi:[1,1,1]
	v_cndmask_b32_e64 v162, v162, v171, s[66:67]
	s_waitcnt lgkmcnt(13)
	v_pk_fma_f32 v[144:145], v[144:145], v[70:71], v[148:149]
	v_pk_fma_f32 v[146:147], v[146:147], v[72:73], v[150:151]
	s_waitcnt lgkmcnt(9)
	v_pk_mul_f32 v[96:97], v[144:145], v[66:67]
	v_pk_mul_f32 v[98:99], v[144:145], v[0:1]
	v_pk_mul_f32 v[100:101], v[144:145], v[4:5]
	v_pk_mul_f32 v[172:173], v[144:145], v[8:9]
	v_pk_fma_f32 v[96:97], v[146:147], v[68:69], v[96:97]
	v_pk_fma_f32 v[98:99], v[146:147], v[2:3], v[98:99]
	ds_read_b128 v[54:57], v174 offset:42720
	v_pk_fma_f32 v[100:101], v[146:147], v[6:7], v[100:101]
	v_pk_fma_f32 v[172:173], v[146:147], v[10:11], v[172:173]
	v_add_f32_e32 v168, v96, v97
	ds_read_b128 v[58:61], v174 offset:42976
	v_add_f32_e32 v166, v98, v99
	v_add_f32_e32 v169, v100, v101
	v_add_f32_e32 v170, v172, v173
	ds_read_b128 v[62:65], v174 offset:43232
	v_add_f32_dpp v168, v168, v168 row_mirror row_mask:0xf bank_mask:0xf bound_ctrl:1
	v_add_f32_dpp v166, v166, v166 row_mirror row_mask:0xf bank_mask:0xf bound_ctrl:1
	v_add_f32_dpp v169, v169, v169 row_mirror row_mask:0xf bank_mask:0xf bound_ctrl:1
	ds_read_b128 v[78:81], v174 offset:44256
	v_add_f32_dpp v170, v170, v170 row_mirror row_mask:0xf bank_mask:0xf bound_ctrl:1
	s_waitcnt lgkmcnt(11)
	v_pk_mul_f32 v[148:149], v[24:25], v[40:41] op_sel_hi:[1,0]
	v_pk_mul_f32 v[150:151], v[26:27], v[40:41] op_sel_hi:[1,0]
	ds_read_b32 v94, v163 offset:45024
	v_add_f32_dpp v168, v168, v168 row_half_mirror row_mask:0xf bank_mask:0xf bound_ctrl:1
	v_add_f32_dpp v166, v166, v166 row_half_mirror row_mask:0xf bank_mask:0xf bound_ctrl:1
	v_add_f32_dpp v169, v169, v169 row_half_mirror row_mask:0xf bank_mask:0xf bound_ctrl:1
	ds_read_b32 v95, v163 offset:45280
	v_add_f32_dpp v170, v170, v170 row_half_mirror row_mask:0xf bank_mask:0xf bound_ctrl:1
	s_waitcnt lgkmcnt(11)
	v_pk_fma_f32 v[148:149], v[32:33], v[40:41], v[148:149] op_sel:[0,1,0] op_sel_hi:[1,1,1]
	v_pk_fma_f32 v[150:151], v[34:35], v[40:41], v[150:151] op_sel:[0,1,0] op_sel_hi:[1,1,1]
	ds_read_b128 v[86:89], v174 offset:44768
	v_add_f32_dpp v168, v168, v168 quad_perm:[1,0,3,2] row_mask:0xf bank_mask:0xf bound_ctrl:1
	v_add_f32_dpp v166, v166, v166 quad_perm:[1,0,3,2] row_mask:0xf bank_mask:0xf bound_ctrl:1
	v_add_f32_dpp v169, v169, v169 quad_perm:[1,0,3,2] row_mask:0xf bank_mask:0xf bound_ctrl:1
	ds_read_b128 v[90:93], v175 offset:45536
	v_add_f32_dpp v170, v170, v170 quad_perm:[1,0,3,2] row_mask:0xf bank_mask:0xf bound_ctrl:1
	v_add_f32_dpp v168, v168, v168 quad_perm:[2,3,0,1] row_mask:0xf bank_mask:0xf bound_ctrl:1
	v_add_f32_dpp v166, v166, v166 quad_perm:[2,3,0,1] row_mask:0xf bank_mask:0xf bound_ctrl:1
	ds_read_b128 v[74:77], v174 offset:44000
	v_add_f32_dpp v169, v169, v169 quad_perm:[2,3,0,1] row_mask:0xf bank_mask:0xf bound_ctrl:1
	v_add_f32_dpp v170, v170, v170 quad_perm:[2,3,0,1] row_mask:0xf bank_mask:0xf bound_ctrl:1
	s_waitcnt lgkmcnt(13)
	v_fma_f32 v164, v40, v37, v169
	ds_read_b128 v[82:85], v174 offset:44512
	v_fma_f32 v171, v40, v39, v170
	s_waitcnt lgkmcnt(13)
	v_pk_fma_f32 v[148:149], v[20:21], v[166:167], v[148:149] op_sel_hi:[1,0,1]
	v_fma_f32 v167, v166, v36, v164
	ds_read_b128 v[70:73], v174 offset:43744
	v_pk_fma_f32 v[150:151], v[22:23], v[166:167], v[150:151] op_sel_hi:[1,0,1]
	v_fma_f32 v171, v166, v38, v171
	v_cndmask_b32_e64 v162, v162, v168, s[68:69]
	ds_read_b128 v[66:69], v174 offset:43488
	s_waitcnt lgkmcnt(14)
	v_pk_fma_f32 v[148:149], v[28:29], v[166:167], v[148:149] op_sel:[0,1,0] op_sel_hi:[1,1,1]
	v_pk_fma_f32 v[150:151], v[30:31], v[166:167], v[150:151] op_sel:[0,1,0] op_sel_hi:[1,1,1]
	v_cndmask_b32_e64 v162, v162, v171, s[70:71]
	s_waitcnt lgkmcnt(13)
	v_pk_fma_f32 v[144:145], v[144:145], v[16:17], v[148:149]
	v_pk_fma_f32 v[146:147], v[146:147], v[18:19], v[150:151]
	s_waitcnt lgkmcnt(9)
	v_pk_mul_f32 v[96:97], v[144:145], v[12:13]
	v_pk_mul_f32 v[98:99], v[144:145], v[54:55]
	v_pk_mul_f32 v[100:101], v[144:145], v[58:59]
	v_pk_mul_f32 v[172:173], v[144:145], v[62:63]
	v_pk_fma_f32 v[96:97], v[146:147], v[14:15], v[96:97]
	v_pk_fma_f32 v[98:99], v[146:147], v[56:57], v[98:99]
	v_pk_fma_f32 v[100:101], v[146:147], v[60:61], v[100:101]
	v_pk_fma_f32 v[172:173], v[146:147], v[64:65], v[172:173]
	v_add_f32_e32 v168, v96, v97
	v_add_f32_e32 v166, v98, v99
	v_add_f32_e32 v169, v100, v101
	v_add_f32_e32 v170, v172, v173
	v_add_f32_dpp v168, v168, v168 row_mirror row_mask:0xf bank_mask:0xf bound_ctrl:1
	v_add_f32_dpp v166, v166, v166 row_mirror row_mask:0xf bank_mask:0xf bound_ctrl:1
	v_add_f32_dpp v169, v169, v169 row_mirror row_mask:0xf bank_mask:0xf bound_ctrl:1
	v_add_f32_dpp v170, v170, v170 row_mirror row_mask:0xf bank_mask:0xf bound_ctrl:1
	s_waitcnt lgkmcnt(7)
	v_pk_mul_f32 v[148:149], v[78:79], v[94:95] op_sel_hi:[1,0]
	v_pk_mul_f32 v[150:151], v[80:81], v[94:95] op_sel_hi:[1,0]
	v_add_f32_dpp v168, v168, v168 row_half_mirror row_mask:0xf bank_mask:0xf bound_ctrl:1
	v_add_f32_dpp v166, v166, v166 row_half_mirror row_mask:0xf bank_mask:0xf bound_ctrl:1
	v_add_f32_dpp v169, v169, v169 row_half_mirror row_mask:0xf bank_mask:0xf bound_ctrl:1
	v_add_f32_dpp v170, v170, v170 row_half_mirror row_mask:0xf bank_mask:0xf bound_ctrl:1
	s_waitcnt lgkmcnt(5)
	v_pk_fma_f32 v[148:149], v[86:87], v[94:95], v[148:149] op_sel:[0,1,0] op_sel_hi:[1,1,1]
	v_pk_fma_f32 v[150:151], v[88:89], v[94:95], v[150:151] op_sel:[0,1,0] op_sel_hi:[1,1,1]
	v_add_f32_dpp v168, v168, v168 quad_perm:[1,0,3,2] row_mask:0xf bank_mask:0xf bound_ctrl:1
	v_add_f32_dpp v166, v166, v166 quad_perm:[1,0,3,2] row_mask:0xf bank_mask:0xf bound_ctrl:1
	v_add_f32_dpp v169, v169, v169 quad_perm:[1,0,3,2] row_mask:0xf bank_mask:0xf bound_ctrl:1
	v_add_f32_dpp v170, v170, v170 quad_perm:[1,0,3,2] row_mask:0xf bank_mask:0xf bound_ctrl:1
	v_add_f32_dpp v168, v168, v168 quad_perm:[2,3,0,1] row_mask:0xf bank_mask:0xf bound_ctrl:1
	v_add_f32_dpp v166, v166, v166 quad_perm:[2,3,0,1] row_mask:0xf bank_mask:0xf bound_ctrl:1
	v_add_f32_dpp v169, v169, v169 quad_perm:[2,3,0,1] row_mask:0xf bank_mask:0xf bound_ctrl:1
	v_add_f32_dpp v170, v170, v170 quad_perm:[2,3,0,1] row_mask:0xf bank_mask:0xf bound_ctrl:1
	s_waitcnt lgkmcnt(4)
	v_fma_f32 v164, v94, v91, v169
	v_fma_f32 v171, v94, v93, v170
	s_waitcnt lgkmcnt(3)
	v_pk_fma_f32 v[148:149], v[74:75], v[166:167], v[148:149] op_sel_hi:[1,0,1]
	v_fma_f32 v167, v166, v90, v164
	v_pk_fma_f32 v[150:151], v[76:77], v[166:167], v[150:151] op_sel_hi:[1,0,1]
	v_fma_f32 v171, v166, v92, v171
	v_cndmask_b32_e64 v162, v162, v168, s[44:45]
	s_waitcnt lgkmcnt(2)
	v_pk_fma_f32 v[148:149], v[82:83], v[166:167], v[148:149] op_sel:[0,1,0] op_sel_hi:[1,1,1]
	v_pk_fma_f32 v[150:151], v[84:85], v[166:167], v[150:151] op_sel:[0,1,0] op_sel_hi:[1,1,1]
	v_cndmask_b32_e64 v162, v162, v171, s[42:43]
	s_waitcnt lgkmcnt(1)
	v_pk_fma_f32 v[144:145], v[144:145], v[70:71], v[148:149]
	v_pk_fma_f32 v[146:147], v[146:147], v[72:73], v[150:151]
	s_waitcnt lgkmcnt(0)
	v_mov_b64_e32 v[24:25], v[66:67]
	v_mov_b64_e32 v[26:27], v[68:69]
	s_mov_b64 s[92:93], 0
